# StaticOrder tile-header division by gsz(=8) as a shift; scan start-state chain reads all end states in one LDS round trip
# speedup vs baseline: 1.0070x; 1.0032x over previous
;     __host__ __device__ bool next(int i, Unit& u) const {
;         const long L = (long)i * G + c; if (L >= nwg) return false;
;         int wgid = (int)L; { const int q = nwg / NXCD, r = nwg % NXCD, xcd = wgid % NXCD, off = wgid / NXCD; wgid = (xcd < r ? xcd * (q + 1) : r * (q + 1) + (xcd - r) * q) + off; }
;         const int nig = WGM * nN, gid = wgid / nig, fm = gid * WGM, gsz = (nM - fm) < WGM ? (nM - fm) : WGM;
;         u.pm = fm + ((wgid % nig) % gsz); u.pn = (wgid % nig) / gsz; return true;
.LBB0_159:
	s_add_i32 s57, s59, 1
	s_mul_i32 s4, s57, s44
	s_mul_hi_u32 s5, s57, s3
	s_add_i32 s5, s5, s4
	s_mul_i32 s4, s57, s3
	s_add_u32 s18, s4, s2
	s_addc_u32 s19, s5, s81
	v_mov_b64_e32 v[2:3], 0x600
	v_cmp_lt_i64_e64 s[4:5], s[18:19], v[2:3]
	v_mov_b64_e32 v[2:3], 0x5ff
	v_cmp_gt_i64_e32 vcc, s[18:19], v[2:3]
	s_cbranch_vccnz .LBB0_161
	s_ashr_i32 s14, s18, 31
	s_lshr_b32 s14, s14, 29
	s_add_i32 s14, s18, s14
	s_ashr_i32 s15, s14, 3
	s_and_b32 s14, s14, -8
	s_sub_i32 s14, s18, s14
	s_cmp_lt_i32 s14, 0
	s_movk_i32 s16, 0xc1
	s_cselect_b32 s16, s16, 0xc0
	s_mul_i32 s14, s14, s16
	s_add_i32 s14, s14, s15
	s_mul_hi_i32 s15, s14, 0x2aaaaaab
	s_lshr_b32 s16, s15, 31
	s_ashr_i32 s15, s15, 3
	s_add_i32 s15, s15, s16
	s_lshl_b32 s16, s15, 3
	s_sub_i32 s17, 0x100, s16
	s_min_i32 s17, s17, 8
	s_mul_i32 s15, s15, 48
	s_sub_i32 s15, s14, s15
	s_ashr_i32 s14, s15, 3
	s_mul_i32 s17, s14, s17
	s_sub_i32 s15, s15, s17
	s_add_i32 s16, s16, s15

;     __device__ __forceinline__ void fused(const f32x4 (&acc)[2][2][4][2], const pg8::Unit& u, int wr, int wc, int fr, int fq, LAS unsigned char* lds, int wid, int lane) const {
;     ...
;             if (wid == 0) {
;                 const int p = lane, d = bj;
;                 const f32x2 a = AT[((l * NG + g) * 2 + d) * NP + p];
;                 float xr = 0.f, xi = 0.f;
;                 for (int i0 = 0; i0 < 256; i0 += 8) {
;                     float sr[8], si[8];
; #pragma unroll
;                     for (int i = 0; i < 8; ++i) { const int c = d == 0 ? i0 + i : 255 - (i0 + i); sr[i] = T[c * TP + p]; si[i] = T[c * TP + 64 + p]; }
; #pragma unroll
;                     for (int i = 0; i < 8; ++i) { const int c = d == 0 ? i0 + i : 255 - (i0 + i);
;                         T[c * TP + p] = xr; T[c * TP + 64 + p] = xi;
;                         const float nr = a.x * xr - a.y * xi + sr[i]; xi = a.x * xi + a.y * xr + si[i]; xr = nr; }
;                 }
.Lscan_p1_f:
	ds_read_b32 v85, v70
	ds_read_b32 v86, v70 offset:256
	ds_read_b32 v87, v70 offset:528
	ds_read_b32 v88, v70 offset:784
	ds_read_b32 v89, v70 offset:1056
	ds_read_b32 v90, v70 offset:1312
	ds_read_b32 v91, v70 offset:1584
	ds_read_b32 v92, v70 offset:1840
	ds_read_b32 v101, v70 offset:2112
	ds_read_b32 v102, v70 offset:2368
	ds_read_b32 v103, v70 offset:2640
	ds_read_b32 v104, v70 offset:2896
	ds_read_b32 v105, v70 offset:3168
	ds_read_b32 v106, v70 offset:3424
	ds_read_b32 v107, v70 offset:3696
	ds_read_b32 v108, v70 offset:3952
	s_waitcnt lgkmcnt(0)
	ds_write_b32 v70, v68
	ds_write_b32 v70, v69 offset:256
	v_fma_f32 v72, v66, v68, v85
	v_fma_f32 v73, v66, v69, v86
	v_fma_f32 v72, -v67, v69, v72
	v_fma_f32 v69, v67, v68, v73
	v_mov_b32_e32 v68, v72
	ds_write_b32 v70, v68 offset:528
	ds_write_b32 v70, v69 offset:784
	v_fma_f32 v72, v66, v68, v87
	v_fma_f32 v73, v66, v69, v88
	v_fma_f32 v72, -v67, v69, v72
	v_fma_f32 v69, v67, v68, v73
	v_mov_b32_e32 v68, v72
	ds_write_b32 v70, v68 offset:1056
	ds_write_b32 v70, v69 offset:1312
	v_fma_f32 v72, v66, v68, v89
	v_fma_f32 v73, v66, v69, v90
	v_fma_f32 v72, -v67, v69, v72
	v_fma_f32 v69, v67, v68, v73
	v_mov_b32_e32 v68, v72
	ds_write_b32 v70, v68 offset:1584
	ds_write_b32 v70, v69 offset:1840
	v_fma_f32 v72, v66, v68, v91
	v_fma_f32 v73, v66, v69, v92
	v_fma_f32 v72, -v67, v69, v72
	v_fma_f32 v69, v67, v68, v73
	v_mov_b32_e32 v68, v72
	ds_write_b32 v70, v68 offset:2112
	ds_write_b32 v70, v69 offset:2368
	v_fma_f32 v72, v66, v68, v101
	v_fma_f32 v73, v66, v69, v102
	v_fma_f32 v72, -v67, v69, v72
	v_fma_f32 v69, v67, v68, v73
	v_mov_b32_e32 v68, v72
	ds_write_b32 v70, v68 offset:2640
	ds_write_b32 v70, v69 offset:2896
	v_fma_f32 v72, v66, v68, v103
	v_fma_f32 v73, v66, v69, v104
	v_fma_f32 v72, -v67, v69, v72
	v_fma_f32 v69, v67, v68, v73
	v_mov_b32_e32 v68, v72
	ds_write_b32 v70, v68 offset:3168
	ds_write_b32 v70, v69 offset:3424
	v_fma_f32 v72, v66, v68, v105
	v_fma_f32 v73, v66, v69, v106
	v_fma_f32 v72, -v67, v69, v72
	v_fma_f32 v69, v67, v68, v73
	v_mov_b32_e32 v68, v72
	ds_write_b32 v70, v68 offset:3696
	ds_write_b32 v70, v69 offset:3952
	v_fma_f32 v72, v66, v68, v107
	v_fma_f32 v73, v66, v69, v108
	v_fma_f32 v72, -v67, v69, v72
	v_fma_f32 v69, v67, v68, v73
	v_mov_b32_e32 v68, v72
	v_add_u32_e32 v70, 0x1080, v70
	s_sub_i32 s4, s4, 1
	s_cmp_lg_u32 s4, 0
	s_cbranch_scc1 .Lscan_p1_f
	ds_write_b32 v84, v68
	ds_write_b32 v84, v69 offset:256
	s_waitcnt lgkmcnt(0)
	s_barrier
	s_lshr_b32 s5, s10, 6
	s_cmp_eq_u32 s5, 0
	s_cbranch_scc1 .Lscan_end_f
	v_mov_b32_e32 v74, v66
	v_mov_b32_e32 v75, v67
	v_mul_f32_e32 v72, v74, v74
	v_mul_f32_e32 v73, v74, v75
	v_fma_f32 v74, -v75, v75, v72
	v_add_f32_e32 v75, v73, v73
	v_mul_f32_e32 v72, v74, v74
	v_mul_f32_e32 v73, v74, v75
	v_fma_f32 v74, -v75, v75, v72
	v_add_f32_e32 v75, v73, v73
	v_mul_f32_e32 v72, v74, v74
	v_mul_f32_e32 v73, v74, v75
	v_fma_f32 v74, -v75, v75, v72
	v_add_f32_e32 v75, v73, v73
	v_mul_f32_e32 v72, v74, v74
	v_mul_f32_e32 v73, v74, v75
	v_fma_f32 v74, -v75, v75, v72
	v_add_f32_e32 v75, v73, v73
	v_mul_f32_e32 v72, v74, v74
	v_mul_f32_e32 v73, v74, v75
	v_fma_f32 v74, -v75, v75, v72
	v_add_f32_e32 v75, v73, v73
	v_mov_b32_e32 v76, 0
	v_mov_b32_e32 v77, 0
	v_lshl_add_u32 v84, v130, 2, 0
	v_add_u32_e32 v84, 0x21000, v84
	ds_read_b32 v85, v84 offset:0
	ds_read_b32 v86, v84 offset:256
	ds_read_b32 v87, v84 offset:512
	ds_read_b32 v88, v84 offset:768
	ds_read_b32 v89, v84 offset:1024
	ds_read_b32 v90, v84 offset:1280
	ds_read_b32 v91, v84 offset:1536
	ds_read_b32 v92, v84 offset:1792
	ds_read_b32 v101, v84 offset:2048
	ds_read_b32 v102, v84 offset:2304
	ds_read_b32 v103, v84 offset:2560
	ds_read_b32 v104, v84 offset:2816
	ds_read_b32 v105, v84 offset:3072
	ds_read_b32 v106, v84 offset:3328
	s_waitcnt lgkmcnt(0)
	v_fma_f32 v72, v74, v76, v85
	v_fma_f32 v73, v74, v77, v86
	v_fma_f32 v72, -v75, v77, v72
	v_fma_f32 v77, v75, v76, v73
	v_mov_b32_e32 v76, v72
	s_cmp_eq_u32 s5, 1
	s_cbranch_scc1 .Lscan_xd_f
	v_fma_f32 v72, v74, v76, v87
	v_fma_f32 v73, v74, v77, v88
	v_fma_f32 v72, -v75, v77, v72
	v_fma_f32 v77, v75, v76, v73
	v_mov_b32_e32 v76, v72
	s_cmp_eq_u32 s5, 2
	s_cbranch_scc1 .Lscan_xd_f
	v_fma_f32 v72, v74, v76, v89
	v_fma_f32 v73, v74, v77, v90
	v_fma_f32 v72, -v75, v77, v72
	v_fma_f32 v77, v75, v76, v73
	v_mov_b32_e32 v76, v72
	s_cmp_eq_u32 s5, 3
	s_cbranch_scc1 .Lscan_xd_f
	v_fma_f32 v72, v74, v76, v91
	v_fma_f32 v73, v74, v77, v92
	v_fma_f32 v72, -v75, v77, v72
	v_fma_f32 v77, v75, v76, v73
	v_mov_b32_e32 v76, v72
	s_cmp_eq_u32 s5, 4
	s_cbranch_scc1 .Lscan_xd_f
	v_fma_f32 v72, v74, v76, v101
	v_fma_f32 v73, v74, v77, v102
	v_fma_f32 v72, -v75, v77, v72
	v_fma_f32 v77, v75, v76, v73
	v_mov_b32_e32 v76, v72
	s_cmp_eq_u32 s5, 5
	s_cbranch_scc1 .Lscan_xd_f
	v_fma_f32 v72, v74, v76, v103
	v_fma_f32 v73, v74, v77, v104
	v_fma_f32 v72, -v75, v77, v72
	v_fma_f32 v77, v75, v76, v73
	v_mov_b32_e32 v76, v72
	s_cmp_eq_u32 s5, 6
	s_cbranch_scc1 .Lscan_xd_f
	v_fma_f32 v72, v74, v76, v105
	v_fma_f32 v73, v74, v77, v106
	v_fma_f32 v72, -v75, v77, v72
	v_fma_f32 v77, v75, v76, v73
	v_mov_b32_e32 v76, v72
.Lscan_xd_f:
	v_mov_b32_e32 v78, 1.0
	v_mov_b32_e32 v79, 0
	v_mov_b32_e32 v70, v80
	s_mov_b32 s4, 4

;     __device__ __forceinline__ void fused(const f32x4 (&acc)[2][2][4][2], const pg8::Unit& u, int wr, int wc, int fr, int fq, LAS unsigned char* lds, int wid, int lane) const {
;     ...
;             if (wid == 0) {
;                 const int p = lane, d = bj;
;                 const f32x2 a = AT[((l * NG + g) * 2 + d) * NP + p];
;                 float xr = 0.f, xi = 0.f;
;                 for (int i0 = 0; i0 < 256; i0 += 8) {
;                     float sr[8], si[8];
; #pragma unroll
;                     for (int i = 0; i < 8; ++i) { const int c = d == 0 ? i0 + i : 255 - (i0 + i); sr[i] = T[c * TP + p]; si[i] = T[c * TP + 64 + p]; }
; #pragma unroll
;                     for (int i = 0; i < 8; ++i) { const int c = d == 0 ? i0 + i : 255 - (i0 + i);
;                         T[c * TP + p] = xr; T[c * TP + 64 + p] = xi;
;                         const float nr = a.x * xr - a.y * xi + sr[i]; xi = a.x * xi + a.y * xr + si[i]; xr = nr; }
;                 }
;             }
.Lscan_p1_b:
	ds_read_b32 v19, v6 offset:3696
	ds_read_b32 v20, v6 offset:3952
	ds_read_b32 v21, v6 offset:3168
	ds_read_b32 v22, v6 offset:3424
	ds_read_b32 v23, v6 offset:2640
	ds_read_b32 v24, v6 offset:2896
	ds_read_b32 v25, v6 offset:2112
	ds_read_b32 v26, v6 offset:2368
	ds_read_b32 v27, v6 offset:1584
	ds_read_b32 v28, v6 offset:1840
	ds_read_b32 v29, v6 offset:1056
	ds_read_b32 v30, v6 offset:1312
	ds_read_b32 v31, v6 offset:528
	ds_read_b32 v32, v6 offset:784
	ds_read_b32 v33, v6
	ds_read_b32 v34, v6 offset:256
	s_waitcnt lgkmcnt(0)
	ds_write_b32 v6, v4 offset:3696
	ds_write_b32 v6, v5 offset:3952
	v_fma_f32 v8, v2, v4, v19
	v_fma_f32 v9, v2, v5, v20
	v_fma_f32 v8, -v3, v5, v8
	v_fma_f32 v5, v3, v4, v9
	v_mov_b32_e32 v4, v8
	ds_write_b32 v6, v4 offset:3168
	ds_write_b32 v6, v5 offset:3424
	v_fma_f32 v8, v2, v4, v21
	v_fma_f32 v9, v2, v5, v22
	v_fma_f32 v8, -v3, v5, v8
	v_fma_f32 v5, v3, v4, v9
	v_mov_b32_e32 v4, v8
	ds_write_b32 v6, v4 offset:2640
	ds_write_b32 v6, v5 offset:2896
	v_fma_f32 v8, v2, v4, v23
	v_fma_f32 v9, v2, v5, v24
	v_fma_f32 v8, -v3, v5, v8
	v_fma_f32 v5, v3, v4, v9
	v_mov_b32_e32 v4, v8
	ds_write_b32 v6, v4 offset:2112
	ds_write_b32 v6, v5 offset:2368
	v_fma_f32 v8, v2, v4, v25
	v_fma_f32 v9, v2, v5, v26
	v_fma_f32 v8, -v3, v5, v8
	v_fma_f32 v5, v3, v4, v9
	v_mov_b32_e32 v4, v8
	ds_write_b32 v6, v4 offset:1584
	ds_write_b32 v6, v5 offset:1840
	v_fma_f32 v8, v2, v4, v27
	v_fma_f32 v9, v2, v5, v28
	v_fma_f32 v8, -v3, v5, v8
	v_fma_f32 v5, v3, v4, v9
	v_mov_b32_e32 v4, v8
	ds_write_b32 v6, v4 offset:1056
	ds_write_b32 v6, v5 offset:1312
	v_fma_f32 v8, v2, v4, v29
	v_fma_f32 v9, v2, v5, v30
	v_fma_f32 v8, -v3, v5, v8
	v_fma_f32 v5, v3, v4, v9
	v_mov_b32_e32 v4, v8
	ds_write_b32 v6, v4 offset:528
	ds_write_b32 v6, v5 offset:784
	v_fma_f32 v8, v2, v4, v31
	v_fma_f32 v9, v2, v5, v32
	v_fma_f32 v8, -v3, v5, v8
	v_fma_f32 v5, v3, v4, v9
	v_mov_b32_e32 v4, v8
	ds_write_b32 v6, v4
	ds_write_b32 v6, v5 offset:256
	v_fma_f32 v8, v2, v4, v33
	v_fma_f32 v9, v2, v5, v34
	v_fma_f32 v8, -v3, v5, v8
	v_fma_f32 v5, v3, v4, v9
	v_mov_b32_e32 v4, v8
	v_add_u32_e32 v6, 0xffffef80, v6
	s_sub_i32 s0, s0, 1
	s_cmp_lg_u32 s0, 0
	s_cbranch_scc1 .Lscan_p1_b
	ds_write_b32 v18, v4
	ds_write_b32 v18, v5 offset:256
	s_waitcnt lgkmcnt(0)
	s_barrier
	s_lshr_b32 s1, s10, 6
	s_cmp_eq_u32 s1, 0
	s_cbranch_scc1 .Lscan_end_b
	v_mov_b32_e32 v10, v2
	v_mov_b32_e32 v11, v3
	v_mul_f32_e32 v8, v10, v10
	v_mul_f32_e32 v9, v10, v11
	v_fma_f32 v10, -v11, v11, v8
	v_add_f32_e32 v11, v9, v9
	v_mul_f32_e32 v8, v10, v10
	v_mul_f32_e32 v9, v10, v11
	v_fma_f32 v10, -v11, v11, v8
	v_add_f32_e32 v11, v9, v9
	v_mul_f32_e32 v8, v10, v10
	v_mul_f32_e32 v9, v10, v11
	v_fma_f32 v10, -v11, v11, v8
	v_add_f32_e32 v11, v9, v9
	v_mul_f32_e32 v8, v10, v10
	v_mul_f32_e32 v9, v10, v11
	v_fma_f32 v10, -v11, v11, v8
	v_add_f32_e32 v11, v9, v9
	v_mul_f32_e32 v8, v10, v10
	v_mul_f32_e32 v9, v10, v11
	v_fma_f32 v10, -v11, v11, v8
	v_add_f32_e32 v11, v9, v9
	v_mov_b32_e32 v12, 0
	v_mov_b32_e32 v13, 0
	v_lshl_add_u32 v18, v130, 2, 0
	v_add_u32_e32 v18, 0x21000, v18
	ds_read_b32 v19, v18 offset:0
	ds_read_b32 v20, v18 offset:256
	ds_read_b32 v21, v18 offset:512
	ds_read_b32 v22, v18 offset:768
	ds_read_b32 v23, v18 offset:1024
	ds_read_b32 v24, v18 offset:1280
	ds_read_b32 v25, v18 offset:1536
	ds_read_b32 v26, v18 offset:1792
	ds_read_b32 v27, v18 offset:2048
	ds_read_b32 v28, v18 offset:2304
	ds_read_b32 v29, v18 offset:2560
	ds_read_b32 v30, v18 offset:2816
	ds_read_b32 v31, v18 offset:3072
	ds_read_b32 v32, v18 offset:3328
	s_waitcnt lgkmcnt(0)
	v_fma_f32 v8, v10, v12, v19
	v_fma_f32 v9, v10, v13, v20
	v_fma_f32 v8, -v11, v13, v8
	v_fma_f32 v13, v11, v12, v9
	v_mov_b32_e32 v12, v8
	s_cmp_eq_u32 s1, 1
	s_cbranch_scc1 .Lscan_xd_b
	v_fma_f32 v8, v10, v12, v21
	v_fma_f32 v9, v10, v13, v22
	v_fma_f32 v8, -v11, v13, v8
	v_fma_f32 v13, v11, v12, v9
	v_mov_b32_e32 v12, v8
	s_cmp_eq_u32 s1, 2
	s_cbranch_scc1 .Lscan_xd_b
	v_fma_f32 v8, v10, v12, v23
	v_fma_f32 v9, v10, v13, v24
	v_fma_f32 v8, -v11, v13, v8
	v_fma_f32 v13, v11, v12, v9
	v_mov_b32_e32 v12, v8
	s_cmp_eq_u32 s1, 3
	s_cbranch_scc1 .Lscan_xd_b
	v_fma_f32 v8, v10, v12, v25
	v_fma_f32 v9, v10, v13, v26
	v_fma_f32 v8, -v11, v13, v8
	v_fma_f32 v13, v11, v12, v9
	v_mov_b32_e32 v12, v8
	s_cmp_eq_u32 s1, 4
	s_cbranch_scc1 .Lscan_xd_b
	v_fma_f32 v8, v10, v12, v27
	v_fma_f32 v9, v10, v13, v28
	v_fma_f32 v8, -v11, v13, v8
	v_fma_f32 v13, v11, v12, v9
	v_mov_b32_e32 v12, v8
	s_cmp_eq_u32 s1, 5
	s_cbranch_scc1 .Lscan_xd_b
	v_fma_f32 v8, v10, v12, v29
	v_fma_f32 v9, v10, v13, v30
	v_fma_f32 v8, -v11, v13, v8
	v_fma_f32 v13, v11, v12, v9
	v_mov_b32_e32 v12, v8
	s_cmp_eq_u32 s1, 6
	s_cbranch_scc1 .Lscan_xd_b
	v_fma_f32 v8, v10, v12, v31
	v_fma_f32 v9, v10, v13, v32
	v_fma_f32 v8, -v11, v13, v8
	v_fma_f32 v13, v11, v12, v9
	v_mov_b32_e32 v12, v8
.Lscan_xd_b:
	v_mov_b32_e32 v14, 1.0
	v_mov_b32_e32 v15, 0
	v_mov_b32_e32 v6, v16
	s_mov_b32 s0, 4

;     __host__ __device__ bool next(int i, Unit& u) const {
;         const long L = (long)i * G + c; if (L >= nwg) return false;
;         int wgid = (int)L; { const int q = nwg / NXCD, r = nwg % NXCD, xcd = wgid % NXCD, off = wgid / NXCD; wgid = (xcd < r ? xcd * (q + 1) : r * (q + 1) + (xcd - r) * q) + off; }
;         const int nig = WGM * nN, gid = wgid / nig, fm = gid * WGM, gsz = (nM - fm) < WGM ? (nM - fm) : WGM;
;         u.pm = fm + ((wgid % nig) % gsz); u.pn = (wgid % nig) / gsz; return true;
.LBB0_385:
	s_ashr_i32 s12, s14, 3
	s_add_i32 s12, s16, s12
	s_ashr_i32 s13, s12, 31
	s_lshr_b32 s13, s13, 28
	s_add_i32 s13, s12, s13
	s_ashr_i32 s14, s13, 4
	s_lshl_b32 s14, s14, 3
	s_sub_i32 s15, 0x100, s14
	s_min_i32 s15, s15, 8
	s_and_b32 s13, s13, -16
	s_sub_i32 s13, s12, s13
	s_ashr_i32 s12, s13, 3
	s_mul_i32 s15, s12, s15
	s_sub_i32 s13, s13, s15
	s_add_i32 s14, s14, s13

;     __host__ __device__ bool next(int i, Unit& u) const {
;         const long L = (long)i * G + c; if (L >= nwg) return false;
;         int wgid = (int)L; { const int q = nwg / NXCD, r = nwg % NXCD, xcd = wgid % NXCD, off = wgid / NXCD; wgid = (xcd < r ? xcd * (q + 1) : r * (q + 1) + (xcd - r) * q) + off; }
;         const int nig = WGM * nN, gid = wgid / nig, fm = gid * WGM, gsz = (nM - fm) < WGM ? (nM - fm) : WGM;
;         u.pm = fm + ((wgid % nig) % gsz); u.pn = (wgid % nig) / gsz; return true;
.LBB0_462:
	s_ashr_i32 s11, s11, 3
	s_add_i32 s11, s21, s11
	s_ashr_i32 s13, s11, 31
	s_lshr_b32 s13, s13, 27
	s_add_i32 s13, s11, s13
	s_ashr_i32 s21, s13, 5
	s_lshl_b32 s21, s21, 3
	s_sub_i32 s22, 0x100, s21
	s_min_i32 s23, s22, 8
	s_andn2_b32 s13, s13, 31
	s_sub_i32 s11, s11, s13
	s_ashr_i32 s22, s11, 3
	s_mul_i32 s13, s22, s23
	s_sub_i32 s11, s11, s13
	s_add_i32 s24, s21, s11

;     __host__ __device__ bool next(int i, Unit& u) const {
;         const long L = (long)i * G + c; if (L >= nwg) return false;
;         int wgid = (int)L; { const int q = nwg / NXCD, r = nwg % NXCD, xcd = wgid % NXCD, off = wgid / NXCD; wgid = (xcd < r ? xcd * (q + 1) : r * (q + 1) + (xcd - r) * q) + off; }
;         const int nig = WGM * nN, gid = wgid / nig, fm = gid * WGM, gsz = (nM - fm) < WGM ? (nM - fm) : WGM;
;         u.pm = fm + ((wgid % nig) % gsz); u.pn = (wgid % nig) / gsz; return true;
.LBB0_661:
	s_ashr_i32 s6, s13, 3
	s_add_i32 s6, s20, s6
	s_ashr_i32 s7, s6, 31
	s_lshr_b32 s7, s7, 27
	s_add_i32 s7, s6, s7
	s_ashr_i32 s13, s7, 5
	s_lshl_b32 s19, s13, 3
	s_sub_i32 s13, 0x100, s19
	s_min_i32 s20, s13, 8
	s_andn2_b32 s7, s7, 31
	s_sub_i32 s6, s6, s7
	s_ashr_i32 s13, s6, 3
	s_mul_i32 s7, s13, s20
	s_sub_i32 s6, s6, s7
	s_add_i32 s48, s19, s6

;     __host__ __device__ bool next(int i, Unit& u) const {
;         const long L = (long)i * G + c; if (L >= nwg) return false;
;         int wgid = (int)L; { const int q = nwg / NXCD, r = nwg % NXCD, xcd = wgid % NXCD, off = wgid / NXCD; wgid = (xcd < r ? xcd * (q + 1) : r * (q + 1) + (xcd - r) * q) + off; }
;         const int nig = WGM * nN, gid = wgid / nig, fm = gid * WGM, gsz = (nM - fm) < WGM ? (nM - fm) : WGM;
;         u.pm = fm + ((wgid % nig) % gsz); u.pn = (wgid % nig) / gsz; return true;
.LBB0_727:
	s_ashr_i32 s6, s14, 3
	s_add_i32 s6, s16, s6
	s_ashr_i32 s7, s6, 31
	s_lshr_b32 s7, s7, 27
	s_add_i32 s7, s6, s7
	s_ashr_i32 s14, s7, 5
	s_lshl_b32 s14, s14, 3
	s_sub_i32 s15, 0x100, s14
	s_min_i32 s15, s15, 8
	s_andn2_b32 s7, s7, 31
	s_sub_i32 s6, s6, s7
	s_ashr_i32 s74, s6, 3
	s_mul_i32 s7, s74, s15
	s_sub_i32 s6, s6, s7
	s_add_i32 s75, s14, s6
